# attention loop: packed f32 VALU ops (v_pk_mul/add/fma_f32) split into scalar pairs
# baseline (speedup 1.0000x reference)
.LBB0_318:
	s_or_b64 exec, exec, s[24:25]
	s_waitcnt vmcnt(2)
	v_lshlrev_b32_e32 v78, 16, v32
	v_and_b32_e32 v79, 0xffff0000, v32
	v_lshlrev_b32_e32 v74, 16, v33
	v_and_b32_e32 v75, 0xffff0000, v33
	v_mul_f32_e32 v80, v78, v78
	v_mul_f32_e32 v81, v79, v79
	v_mul_f32_e32 v76, v74, v74
	v_mul_f32_e32 v77, v75, v75
	v_add_f32_e32 v0, v80, v81
	v_lshlrev_b32_e32 v70, 16, v34
	v_and_b32_e32 v71, 0xffff0000, v34
	v_add_f32_e32 v0, v76, v0
	v_mul_f32_e32 v72, v70, v70
	v_mul_f32_e32 v73, v71, v71
	v_add_f32_e32 v0, v77, v0
	v_lshlrev_b32_e32 v2, 16, v35
	v_and_b32_e32 v3, 0xffff0000, v35
	v_add_f32_e32 v0, v72, v0
	v_mul_f32_e32 v68, v2, v2
	v_mul_f32_e32 v69, v3, v3
	v_add_f32_e32 v0, v73, v0
	v_add_f32_e32 v0, v68, v0
	v_add_f32_e32 v0, v69, v0
	ds_bpermute_b32 v68, v174, v0
	v_lshlrev_b32_e32 v86, 16, v28
	v_and_b32_e32 v87, 0xffff0000, v28
	v_lshlrev_b32_e32 v102, 16, v36
	v_and_b32_e32 v103, 0xffff0000, v36
	s_waitcnt lgkmcnt(0)
	v_add_f32_e32 v0, v0, v68
	ds_bpermute_b32 v68, v175, v0
	v_lshlrev_b32_e32 v82, 16, v29
	v_and_b32_e32 v83, 0xffff0000, v29
	v_mul_f32_e32 v88, v86, v86
	v_mul_f32_e32 v89, v87, v87
	v_lshlrev_b32_e32 v98, 16, v37
	s_waitcnt lgkmcnt(0)
	v_add_f32_e32 v0, v0, v68
	ds_bpermute_b32 v68, v176, v0
	v_and_b32_e32 v99, 0xffff0000, v37
	v_mul_f32_e32 v104, v102, v102
	v_mul_f32_e32 v105, v103, v103
	v_mul_f32_e32 v84, v82, v82
	v_mul_f32_e32 v85, v83, v83
	v_mul_f32_e32 v100, v98, v98
	v_mul_f32_e32 v101, v99, v99
	v_mov_b32_e32 v106, v104
	v_mov_b32_e32 v107, v88
	v_mov_b32_e32 v88, v105
	s_waitcnt lgkmcnt(0)
	v_add_f32_e32 v0, v0, v68
	v_lshlrev_b32_e32 v76, 16, v30
	v_and_b32_e32 v77, 0xffff0000, v30
	v_lshlrev_b32_e32 v94, 16, v38
	v_and_b32_e32 v95, 0xffff0000, v38
	v_add_f32_e32 v88, v106, v88
	v_add_f32_e32 v89, v107, v89
	v_mov_b32_e32 v104, v100
	v_mov_b32_e32 v105, v84
	v_fmamk_f32 v0, v0, 0x3c800000, v205
	v_mul_f32_e32 v80, v76, v76
	v_mul_f32_e32 v81, v77, v77
	v_mul_f32_e32 v96, v94, v94
	v_mul_f32_e32 v97, v95, v95
	v_add_f32_e32 v88, v104, v88
	v_add_f32_e32 v89, v105, v89
	v_mov_b32_e32 v84, v101
	v_lshlrev_b32_e32 v72, 16, v31
	v_mul_f32_e32 v68, 0x4b800000, v0
	v_cmp_gt_f32_e32 vcc, s83, v0
	v_and_b32_e32 v73, 0xffff0000, v31
	v_lshlrev_b32_e32 v90, 16, v39
	v_and_b32_e32 v91, 0xffff0000, v39
	v_add_f32_e32 v84, v84, v88
	v_add_f32_e32 v85, v85, v89
	v_mov_b32_e32 v88, v96
	v_mov_b32_e32 v89, v80
	v_cndmask_b32_e32 v0, v0, v68, vcc
	v_mul_f32_e32 v68, v72, v72
	v_mul_f32_e32 v69, v73, v73
	v_mul_f32_e32 v92, v90, v90
	v_mul_f32_e32 v93, v91, v91
	v_add_f32_e32 v84, v88, v84
	v_add_f32_e32 v85, v89, v85
	v_mov_b32_e32 v80, v97
	v_add_f32_e32 v80, v80, v84
	v_add_f32_e32 v81, v81, v85
	v_mov_b32_e32 v84, v92
	v_mov_b32_e32 v85, v68
	v_add_f32_e32 v80, v84, v80
	v_add_f32_e32 v81, v85, v81
	v_mov_b32_e32 v68, v93
	v_add_f32_e32 v68, v68, v80
	v_add_f32_e32 v69, v69, v81
	ds_bpermute_b32 v81, v174, v69
	ds_bpermute_b32 v80, v174, v68
	v_rsq_f32_e32 v0, v0
	s_mov_b32 s0, 0x358637bd
	s_mov_b32 s24, 0x3c800000
	v_lshlrev_b32_e32 v96, 16, v40
	v_mul_f32_e32 v84, 0x45800000, v0
	s_waitcnt lgkmcnt(0)
	v_add_f32_e32 v80, v68, v80
	v_add_f32_e32 v81, v69, v81
	v_cndmask_b32_e32 v0, v0, v84, vcc
	ds_bpermute_b32 v85, v175, v81
	ds_bpermute_b32 v84, v175, v80
	v_mul_f32_e32 v74, v0, v74
	v_mul_f32_e32 v75, v0, v75
	v_mul_f32_e32 v78, v0, v78
	v_mul_f32_e32 v79, v0, v79
	v_mul_f32_e32 v74, v10, v74
	v_mul_f32_e32 v75, v11, v75
	v_mul_f32_e32 v78, v8, v78
	v_mul_f32_e32 v79, v9, v79
	v_cvt_pk_bf16_f32 v69, v74, v75
	s_waitcnt lgkmcnt(0)
	v_add_f32_e32 v74, v80, v84
	v_add_f32_e32 v75, v81, v85
	v_cvt_pk_bf16_f32 v68, v78, v79
	ds_bpermute_b32 v79, v176, v75
	ds_bpermute_b32 v78, v176, v74
	v_mov_b64_e32 v[84:85], s[0:1]
	v_mul_f32_e32 v70, v0, v70
	v_mul_f32_e32 v71, v0, v71
	v_mul_f32_e32 v2, v0, v2
	v_mul_f32_e32 v3, v0, v3
	v_mul_f32_e32 v70, v4, v70
	v_mul_f32_e32 v71, v5, v71
	s_waitcnt lgkmcnt(0)
	v_add_f32_e32 v74, v74, v78
	v_add_f32_e32 v75, v75, v79
	v_mul_f32_e32 v2, v6, v2
	v_mul_f32_e32 v3, v7, v3
	v_fma_f32 v74, v74, s24, v84
	v_fma_f32 v75, v75, s24, v84
	v_cvt_pk_bf16_f32 v70, v70, v71
	v_mul_f32_e32 v0, 0x4b800000, v75
	v_cmp_gt_f32_e32 vcc, s83, v75
	v_cvt_pk_bf16_f32 v71, v2, v3
	ds_write_b128 v233, v[68:71]
	v_cndmask_b32_e32 v0, v75, v0, vcc
	v_rsq_f32_e32 v0, v0
	s_waitcnt vmcnt(0)
	v_and_b32_e32 v75, 0xffff0000, v64
	v_lshlrev_b32_e32 v92, 16, v41
	v_and_b32_e32 v93, 0xffff0000, v41
	v_mul_f32_e32 v2, 0x45800000, v0
	v_cndmask_b32_e32 v0, v0, v2, vcc
	v_mul_f32_e32 v2, v0, v86
	v_mul_f32_e32 v3, v0, v87
	v_mul_f32_e32 v2, v8, v2
	v_mul_f32_e32 v3, v9, v3
	v_cmp_gt_f32_e32 vcc, s83, v74
	v_cvt_pk_bf16_f32 v68, v2, v3
	v_mul_f32_e32 v2, v0, v82
	v_mul_f32_e32 v3, v0, v83
	v_mul_f32_e32 v2, v10, v2
	v_mul_f32_e32 v3, v11, v3
	v_and_b32_e32 v97, 0xffff0000, v40
	v_cvt_pk_bf16_f32 v69, v2, v3
	v_mul_f32_e32 v2, v0, v76
	v_mul_f32_e32 v3, v0, v77
	v_mul_f32_e32 v2, v4, v2
	v_mul_f32_e32 v3, v5, v3
	v_lshlrev_b32_e32 v76, 16, v63
	v_cvt_pk_bf16_f32 v70, v2, v3
	v_mul_f32_e32 v2, v0, v72
	v_mul_f32_e32 v3, v0, v73
	v_mul_f32_e32 v0, 0x4b800000, v74
	v_cndmask_b32_e32 v0, v74, v0, vcc
	v_rsq_f32_e32 v0, v0
	v_mul_f32_e32 v2, v6, v2
	v_mul_f32_e32 v3, v7, v3
	v_and_b32_e32 v77, 0xffff0000, v63
	v_cvt_pk_bf16_f32 v71, v2, v3
	v_mul_f32_e32 v2, 0x45800000, v0
	v_cndmask_b32_e32 v0, v0, v2, vcc
	v_mul_f32_e32 v2, v0, v102
	v_mul_f32_e32 v3, v0, v103
	v_mul_f32_e32 v2, v8, v2
	v_mul_f32_e32 v3, v9, v3
	ds_write_b128 v234, v[68:71]
	v_cvt_pk_bf16_f32 v68, v2, v3
	v_mul_f32_e32 v2, v0, v98
	v_mul_f32_e32 v3, v0, v99
	v_mul_f32_e32 v2, v10, v2
	v_mul_f32_e32 v3, v11, v3
	v_lshlrev_b32_e32 v72, 16, v65
	v_cvt_pk_bf16_f32 v69, v2, v3
	v_mul_f32_e32 v2, v0, v94
	v_mul_f32_e32 v3, v0, v95
	v_mul_f32_e32 v2, v4, v2
	v_mul_f32_e32 v3, v5, v3
	v_and_b32_e32 v73, 0xffff0000, v65
	v_cvt_pk_bf16_f32 v70, v2, v3
	v_mul_f32_e32 v2, v0, v90
	v_mul_f32_e32 v3, v0, v91
	v_mul_f32_e32 v2, v6, v2
	v_mul_f32_e32 v3, v7, v3
	v_lshlrev_b32_e32 v74, 16, v64
	v_cvt_pk_bf16_f32 v71, v2, v3
	ds_write_b128 v235, v[68:71]
	v_lshlrev_b32_e32 v68, 16, v67
	v_and_b32_e32 v69, 0xffff0000, v67
	v_lshlrev_b32_e32 v70, 16, v66
	v_and_b32_e32 v71, 0xffff0000, v66
	v_mul_f32_e32 v78, v68, v68
	v_mul_f32_e32 v79, v69, v69
	v_mul_f32_e32 v80, v70, v70
	v_mul_f32_e32 v81, v71, v71
	v_fma_f32 v100, v76, v76, v78
	v_fma_f32 v101, v77, v77, v79
	v_lshlrev_b32_e32 v78, 16, v62
	v_and_b32_e32 v79, 0xffff0000, v62
	v_fma_f32 v102, v78, v78, v80
	v_fma_f32 v103, v79, v79, v81
	v_lshlrev_b32_e32 v80, 16, v61
	v_and_b32_e32 v81, 0xffff0000, v61
	v_mul_f32_e32 v82, v72, v72
	v_mul_f32_e32 v83, v73, v73
	v_mul_f32_e32 v0, v96, v96
	v_fma_f32 v104, v80, v80, v82
	v_fma_f32 v105, v81, v81, v83
	v_lshlrev_b32_e32 v82, 16, v60
	v_and_b32_e32 v83, 0xffff0000, v60
	v_mul_f32_e32 v106, v74, v74
	v_mul_f32_e32 v107, v75, v75
	v_mul_f32_e32 v94, v92, v92
	v_mul_f32_e32 v95, v93, v93
	v_fma_f32 v98, v96, v96, v0
	v_fma_f32 v99, v97, v97, v0
	v_fma_f32 v106, v82, v82, v106
	v_fma_f32 v107, v83, v83, v107
	v_lshlrev_b32_e32 v88, 16, v42
	v_and_b32_e32 v89, 0xffff0000, v42
	v_mov_b32_e32 v108, v106
	v_mov_b32_e32 v109, v94
	v_mov_b32_e32 v98, v107
	v_mul_f32_e32 v90, v88, v88
	v_mul_f32_e32 v91, v89, v89
	v_add_f32_e32 v98, v108, v98
	v_add_f32_e32 v99, v109, v99
	v_mov_b32_e32 v94, v104
	v_lshlrev_b32_e32 v2, 16, v43
	v_and_b32_e32 v3, 0xffff0000, v43
	v_add_f32_e32 v94, v94, v98
	v_add_f32_e32 v95, v95, v99
	v_pk_mov_b32 v[98:99], v[104:105], v[90:91] op_sel:[1,0]
	v_mul_f32_e32 v86, v2, v2
	v_mul_f32_e32 v87, v3, v3
	v_add_f32_e32 v94, v98, v94
	v_add_f32_e32 v95, v99, v95
	v_mov_b32_e32 v90, v102
	v_add_f32_e32 v90, v90, v94
	v_add_f32_e32 v91, v91, v95
	v_pk_mov_b32 v[94:95], v[102:103], v[86:87] op_sel:[1,0]
	v_mov_b32_e32 v86, v100
	v_add_f32_e32 v90, v94, v90
	v_add_f32_e32 v91, v95, v91
	v_and_b32_e32 v0, 0xffff, v44
	v_add_f32_e32 v86, v86, v90
	v_add_f32_e32 v87, v87, v91
	ds_bpermute_b32 v91, v174, v87
	v_mov_b32_e32 v90, v101
	v_lshl_or_b32 v110, v48, 16, v0
	v_lshrrev_b32_e32 v0, 16, v44
	s_mov_b32 s0, 0xffff0000
	s_waitcnt lgkmcnt(0)
	v_add_f32_e32 v86, v90, v86
	v_add_f32_e32 v87, v91, v87
	v_and_or_b32 v111, v48, s0, v0
	v_and_b32_e32 v0, 0xffff, v45
	ds_bpermute_b32 v91, v175, v87
	ds_bpermute_b32 v90, v177, v86
	v_lshl_or_b32 v134, v49, 16, v0
	v_lshrrev_b32_e32 v0, 16, v45
	v_and_or_b32 v135, v49, s0, v0
	v_and_b32_e32 v0, 0xffff, v46
	v_lshl_or_b32 v136, v50, 16, v0
	v_lshrrev_b32_e32 v0, 16, v46
	v_and_or_b32 v137, v50, s0, v0
	v_and_b32_e32 v0, 0xffff, v47
	v_lshl_or_b32 v138, v51, 16, v0
	v_lshrrev_b32_e32 v0, 16, v47
	s_waitcnt lgkmcnt(0)
	v_add_f32_e32 v86, v86, v90
	v_add_f32_e32 v87, v87, v91
	v_and_or_b32 v139, v51, s0, v0
	v_and_b32_e32 v0, 0xffff, v52
	ds_bpermute_b32 v91, v176, v87
	ds_bpermute_b32 v90, v178, v86
	v_lshl_or_b32 v140, v56, 16, v0
	v_lshrrev_b32_e32 v0, 16, v52
	v_and_or_b32 v94, v56, s0, v0
	v_and_b32_e32 v0, 0xffff, v53
	v_lshl_or_b32 v95, v57, 16, v0
	v_lshrrev_b32_e32 v0, 16, v53
	v_and_or_b32 v98, v57, s0, v0
	v_and_b32_e32 v0, 0xffff, v54
	v_lshl_or_b32 v99, v58, 16, v0
	v_lshrrev_b32_e32 v0, 16, v54
	s_waitcnt lgkmcnt(0)
	v_add_f32_e32 v86, v86, v90
	v_add_f32_e32 v87, v87, v91
	v_and_or_b32 v100, v58, s0, v0
	v_and_b32_e32 v0, 0xffff, v55
	v_fma_f32 v85, v87, s24, v84
	v_fma_f32 v84, v86, s24, v84
	v_lshl_or_b32 v101, v59, 16, v0
	v_mul_f32_e32 v0, 0x4b800000, v85
	v_cmp_gt_f32_e32 vcc, s83, v85
	s_add_i32 s59, s58, s46
	s_cmpk_gt_i32 s59, 0xfff
	v_cndmask_b32_e32 v0, v85, v0, vcc
	v_rsq_f32_e32 v0, v0
	v_lshrrev_b32_e32 v85, 16, v55
	v_and_or_b32 v85, v59, s0, v85
	s_mov_b32 s0, 0x800000
	v_mul_f32_e32 v86, 0x45800000, v0
	v_cndmask_b32_e32 v0, v0, v86, vcc
	v_mul_f32_e32 v86, v0, v96
	v_mul_f32_e32 v87, v0, v97
	v_mul_f32_e32 v90, v0, v92
	v_mul_f32_e32 v91, v0, v93
	v_mul_f32_e32 v88, v0, v88
	v_mul_f32_e32 v89, v0, v89
	v_mul_f32_e32 v2, v0, v2
	v_mul_f32_e32 v3, v0, v3
	v_mul_f32_e32 v86, v8, v86
	v_mul_f32_e32 v87, v9, v87
	v_mul_f32_e32 v90, v10, v90
	v_mul_f32_e32 v91, v11, v91
	v_mul_f32_e32 v88, v4, v88
	v_mul_f32_e32 v89, v5, v89
	v_mul_f32_e32 v2, v6, v2
	v_mul_f32_e32 v3, v7, v3
	v_cvt_pk_bf16_f32 v86, v86, v87
	v_cvt_pk_bf16_f32 v87, v90, v91
	v_cvt_pk_bf16_f32 v88, v88, v89
	v_cvt_pk_bf16_f32 v89, v2, v3
	v_add_u32_e32 v0, 0x9000, v237
	ds_write_b128 v236, v[86:89]
	ds_write2_b32 v0, v110, v111 offset1:132
	v_add_u32_e32 v0, 0x9400, v237
	ds_write2_b32 v0, v134, v135 offset0:8 offset1:140
	v_add_u32_e32 v0, 0x9800, v237
	ds_write2_b32 v0, v136, v137 offset0:16 offset1:148
	v_add_u32_e32 v0, 0x9c00, v237
	ds_write2_b32 v0, v138, v139 offset0:24 offset1:156
	v_add_u32_e32 v0, 0x9000, v238
	ds_write2_b32 v0, v140, v94 offset1:132
	v_add_u32_e32 v0, 0x9400, v238
	ds_write2_b32 v0, v95, v98 offset0:8 offset1:140
	v_add_u32_e32 v0, 0x9800, v238
	s_cselect_b64 s[28:29], -1, 0
	v_cmp_gt_f32_e64 s[82:83], s0, v84
	ds_write2_b32 v0, v99, v100 offset0:16 offset1:148
	v_add_u32_e32 v0, 0x9c00, v238
	s_and_b64 vcc, exec, s[28:29]
	ds_write2_b32 v0, v101, v85 offset0:24 offset1:156
	s_cbranch_vccnz .LBB0_333
	s_and_b32 s0, 0xffff, s47
	s_and_b32 s25, s59, 0x7f
	s_ashr_i32 s24, s59, 11
	s_lshr_b32 s0, s25, s0
	s_and_b32 s25, s25, s56
	s_bfe_u32 s34, s59, 0x40007
	s_lshl_b32 s35, s25, 7
	s_lshl_b32 s25, s24, 4
	s_or_b32 s48, s25, s34
	s_ashr_i32 s49, s48, 31
	s_lshl_b64 s[48:49], s[48:49], 14
	s_lshl_b64 s[52:53], s[0:1], s99
	s_add_u32 s52, s52, s48
	s_addc_u32 s53, s53, s49
	s_add_i32 s25, s35, 0xffffff80
	v_mov_b32_e32 v30, v1
	v_mov_b32_e32 v31, v1
	v_add_u32_e32 v0, s25, v129
	v_mov_b32_e32 v28, v1
	v_mov_b32_e32 v29, v1
	v_mov_b64_e32 v[34:35], v[30:31]
	v_cmp_lt_i32_e32 vcc, -1, v0
	v_mov_b64_e32 v[32:33], v[28:29]
	s_and_saveexec_b64 s[54:55], vcc
	s_cbranch_execz .LBB0_321
	v_lshl_add_u64 v[2:3], s[52:53], 0, v[0:1]
	v_lshlrev_b64 v[2:3], 7, v[2:3]
	v_lshl_add_u64 v[2:3], v[122:123], 0, v[2:3]
	global_load_dwordx4 v[32:35], v[2:3], off

.LBB0_334:
	v_mul_f32_e32 v0, 0x4b800000, v84
	v_cndmask_b32_e64 v0, v84, v0, s[82:83]
	v_rsq_f32_e32 v0, v0
	s_waitcnt lgkmcnt(0)
	s_barrier
	v_mul_f32_e32 v84, 0x45800000, v0
	v_cndmask_b32_e64 v0, v0, v84, s[82:83]
	v_mul_f32_e32 v0, 0x3e000000, v0
	v_mul_f32_e32 v0, 0x3fb8aa3b, v0
	v_mul_f32_e32 v76, v0, v76
	v_mul_f32_e32 v77, v0, v77
	v_mul_f32_e32 v74, v0, v74
	v_mul_f32_e32 v75, v0, v75
	v_mul_f32_e32 v76, v14, v76
	v_mul_f32_e32 v77, v15, v77
	v_mul_f32_e32 v74, v24, v74
	v_mul_f32_e32 v75, v25, v75
	v_cvt_pk_bf16_f32 v91, v76, v77
	v_cvt_pk_bf16_f32 v140, v74, v75
	ds_read_b128 v[74:77], v239
	v_mul_f32_e32 v80, v0, v80
	v_mul_f32_e32 v81, v0, v81
	v_mul_f32_e32 v78, v0, v78
	v_mul_f32_e32 v79, v0, v79
	v_mul_f32_e32 v80, v18, v80
	v_mul_f32_e32 v81, v19, v81
	v_mul_f32_e32 v78, v12, v78
	v_mul_f32_e32 v79, v13, v79
	v_cvt_pk_bf16_f32 v89, v80, v81
	v_cvt_pk_bf16_f32 v90, v78, v79
	ds_read_b128 v[78:81], v239 offset:64
	v_mul_f32_e32 v82, v0, v82
	v_mul_f32_e32 v83, v0, v83
	v_mul_f32_e32 v82, v16, v82
	v_mul_f32_e32 v83, v17, v83
	v_mul_f32_e32 v72, v0, v72
	v_mul_f32_e32 v73, v0, v73
	v_mul_f32_e32 v70, v0, v70
	v_mul_f32_e32 v71, v0, v71
	v_cvt_pk_bf16_f32 v88, v82, v83
	v_mul_f32_e32 v72, v26, v72
	v_mul_f32_e32 v73, v27, v73
	v_mul_f32_e32 v70, v20, v70
	v_mul_f32_e32 v71, v21, v71
	v_cvt_pk_bf16_f32 v141, v72, v73
	v_cvt_pk_bf16_f32 v142, v70, v71
	v_mul_f32_e32 v82, v0, v68
	v_mul_f32_e32 v83, v0, v69
	s_waitcnt lgkmcnt(1)
	v_mfma_f32_16x16x32_bf16 v[68:71], v[74:77], v[88:91], 0
	ds_read_b128 v[72:75], v240
	v_mul_f32_e32 v76, v22, v82
	v_mul_f32_e32 v77, v23, v83
	ds_read_b128 v[144:147], v247
	v_cvt_pk_bf16_f32 v143, v76, v77
	s_and_b32 s0, s58, s56
	s_and_b32 s0, s0, 0x7f
	s_waitcnt lgkmcnt(2)
	v_mfma_f32_16x16x32_bf16 v[108:111], v[78:81], v[140:143], v[68:71]
	ds_read_b128 v[76:79], v241
	s_cmp_lg_u32 s0, 0
	s_nop 0
	ds_read_b128 v[68:71], v240 offset:64
	s_waitcnt lgkmcnt(3)
	v_mfma_f32_16x16x32_bf16 v[72:75], v[72:75], v[88:91], 0
	s_waitcnt lgkmcnt(0)
	v_mfma_f32_16x16x32_bf16 v[104:107], v[68:71], v[140:143], v[72:75]
	ds_read_b128 v[68:71], v241 offset:64
	v_mfma_f32_16x16x32_bf16 v[72:75], v[76:79], v[88:91], 0
	ds_read_b128 v[76:79], v242
	s_waitcnt lgkmcnt(1)
	v_mfma_f32_16x16x32_bf16 v[100:103], v[68:71], v[140:143], v[72:75]
	ds_read_b128 v[68:71], v242 offset:64
	s_waitcnt lgkmcnt(1)
	v_mfma_f32_16x16x32_bf16 v[72:75], v[76:79], v[88:91], 0
	ds_read_b128 v[76:79], v243
	s_waitcnt lgkmcnt(1)
	v_mfma_f32_16x16x32_bf16 v[96:99], v[68:71], v[140:143], v[72:75]
	ds_read_b128 v[68:71], v243 offset:64
	s_waitcnt lgkmcnt(1)
	v_mfma_f32_16x16x32_bf16 v[72:75], v[76:79], v[88:91], 0
	ds_read_b128 v[76:79], v244
	s_waitcnt lgkmcnt(1)
	v_mfma_f32_16x16x32_bf16 v[92:95], v[68:71], v[140:143], v[72:75]
	ds_read_b128 v[68:71], v244 offset:64
	s_waitcnt lgkmcnt(1)
	v_mfma_f32_16x16x32_bf16 v[72:75], v[76:79], v[88:91], 0
	ds_read_b128 v[76:79], v245
	s_waitcnt lgkmcnt(1)
	v_mfma_f32_16x16x32_bf16 v[84:87], v[68:71], v[140:143], v[72:75]
	ds_read_b128 v[68:71], v245 offset:64
	s_waitcnt lgkmcnt(1)
	v_mfma_f32_16x16x32_bf16 v[72:75], v[76:79], v[88:91], 0
	ds_read_b128 v[76:79], v246
	s_waitcnt lgkmcnt(1)
	v_mfma_f32_16x16x32_bf16 v[80:83], v[68:71], v[140:143], v[72:75]
	ds_read_b128 v[68:71], v246 offset:64
	s_waitcnt lgkmcnt(1)
	v_mfma_f32_16x16x32_bf16 v[72:75], v[76:79], v[88:91], 0
	s_waitcnt lgkmcnt(0)
	v_mfma_f32_16x16x32_bf16 v[76:79], v[68:71], v[140:143], v[72:75]
	ds_read_b128 v[68:71], v247 offset:64
	v_mfma_f32_16x16x32_bf16 v[72:75], v[144:147], v[88:91], 0
	s_waitcnt lgkmcnt(0)
	v_mfma_f32_16x16x32_bf16 v[72:75], v[68:71], v[140:143], v[72:75]
	s_cbranch_scc0 .LBB0_352
	v_mov_b32_e32 v68, 0xff800000
	v_mov_b32_e32 v69, 0xff800000
	v_mov_b32_e32 v70, 0xff800000
	v_mov_b32_e32 v71, 0xff800000
	v_mov_b32_e32 v88, 0xff800000
	v_mov_b32_e32 v89, 0xff800000
	v_mov_b32_e32 v90, 0xff800000
	v_mov_b32_e32 v91, 0xff800000
	s_mov_b64 s[24:25], exec
	s_and_b64 exec, s[24:25], s[8:9]
	ds_read_b32 v68, v183
	s_and_b64 exec, s[24:25], s[10:11]
	ds_read_b32 v69, v184
	s_and_b64 exec, s[24:25], s[12:13]
	ds_read_b32 v70, v185
	s_and_b64 exec, s[24:25], s[14:15]
	ds_read_b32 v71, v186
	s_and_b64 exec, s[24:25], s[16:17]
	ds_read_b32 v88, v187
	s_and_b64 exec, s[24:25], s[18:19]
	ds_read_b32 v89, v188
	s_and_b64 exec, s[24:25], s[20:21]
	ds_read_b32 v90, v189
	s_and_b64 exec, s[24:25], s[22:23]
	ds_read_b32 v91, v190
	s_mov_b64 exec, s[24:25]
	ds_read2_b32 v[142:143], v187 offset0:111 offset1:112
	ds_read2_b32 v[140:141], v187 offset0:109 offset1:110
	ds_read2_b32 v[144:145], v187 offset0:95 offset1:96
	ds_read2_b32 v[146:147], v187 offset0:93 offset1:94
	ds_read2_b32 v[148:149], v187 offset0:79 offset1:80
	ds_read2_b32 v[150:151], v187 offset0:77 offset1:78
	ds_read2_b32 v[152:153], v187 offset0:63 offset1:64
	ds_read2_b32 v[154:155], v187 offset0:61 offset1:62
	ds_read2_b32 v[156:157], v187 offset0:47 offset1:48
	ds_read2_b32 v[158:159], v187 offset0:45 offset1:46
	ds_read2_b32 v[160:161], v187 offset0:31 offset1:32
	ds_read2_b32 v[166:167], v187 offset0:29 offset1:30
	ds_read2_b32 v[168:169], v187 offset0:15 offset1:16
	ds_read2_b32 v[170:171], v187 offset0:13 offset1:14
	s_waitcnt lgkmcnt(14)
	s_and_b64 exec, s[24:25], s[8:9]
	v_add_f32_e32 v68, v108, v68
	s_and_b64 exec, s[24:25], s[10:11]
	v_add_f32_e32 v69, v109, v69
	s_and_b64 exec, s[24:25], s[12:13]
	v_add_f32_e32 v70, v110, v70
	s_and_b64 exec, s[24:25], s[14:15]
	v_add_f32_e32 v71, v111, v71
	s_and_b64 exec, s[24:25], s[16:17]
	v_add_f32_e32 v88, v72, v88
	s_and_b64 exec, s[24:25], s[18:19]
	v_add_f32_e32 v89, v73, v89
	s_and_b64 exec, s[24:25], s[20:21]
	v_add_f32_e32 v90, v74, v90
	s_and_b64 exec, s[24:25], s[22:23]
	v_add_f32_e32 v91, v75, v91
	s_mov_b64 exec, s[24:25]
	s_mov_b32 s24, 0xff800000
	v_max3_f32 v0, v68, s24, v69
	v_max3_f32 v0, v0, v70, v71
	s_waitcnt lgkmcnt(13)
	v_pk_add_f32 v[142:143], v[104:105], v[142:143] op_sel:[0,1] op_sel_hi:[1,0]
	s_waitcnt lgkmcnt(12)
	v_pk_add_f32 v[140:141], v[106:107], v[140:141] op_sel:[0,1] op_sel_hi:[1,0]
	v_max3_f32 v0, v0, v142, v143
	v_max3_f32 v0, v0, v140, v141
	s_waitcnt lgkmcnt(11)
	v_pk_add_f32 v[144:145], v[100:101], v[144:145] op_sel:[0,1] op_sel_hi:[1,0]
	s_waitcnt lgkmcnt(10)
	v_pk_add_f32 v[146:147], v[102:103], v[146:147] op_sel:[0,1] op_sel_hi:[1,0]
	v_max3_f32 v0, v0, v144, v145
	v_max3_f32 v0, v0, v146, v147
	s_waitcnt lgkmcnt(9)
	v_pk_add_f32 v[148:149], v[96:97], v[148:149] op_sel:[0,1] op_sel_hi:[1,0]
	s_waitcnt lgkmcnt(8)
	v_pk_add_f32 v[150:151], v[98:99], v[150:151] op_sel:[0,1] op_sel_hi:[1,0]
	v_max3_f32 v0, v0, v148, v149
	v_max3_f32 v0, v0, v150, v151
	s_waitcnt lgkmcnt(7)
	v_pk_add_f32 v[152:153], v[92:93], v[152:153] op_sel:[0,1] op_sel_hi:[1,0]
	s_waitcnt lgkmcnt(6)
	v_pk_add_f32 v[154:155], v[94:95], v[154:155] op_sel:[0,1] op_sel_hi:[1,0]
	v_max3_f32 v0, v0, v152, v153
	v_max3_f32 v0, v0, v154, v155
	s_waitcnt lgkmcnt(5)
	v_pk_add_f32 v[156:157], v[84:85], v[156:157] op_sel:[0,1] op_sel_hi:[1,0]
	s_waitcnt lgkmcnt(4)
	v_pk_add_f32 v[158:159], v[86:87], v[158:159] op_sel:[0,1] op_sel_hi:[1,0]
	v_max3_f32 v0, v0, v156, v157
	v_max3_f32 v0, v0, v158, v159
	s_waitcnt lgkmcnt(3)
	v_pk_add_f32 v[160:161], v[80:81], v[160:161] op_sel:[0,1] op_sel_hi:[1,0]
	s_waitcnt lgkmcnt(2)
	v_pk_add_f32 v[166:167], v[82:83], v[166:167] op_sel:[0,1] op_sel_hi:[1,0]
	v_max3_f32 v0, v0, v160, v161
	v_max3_f32 v0, v0, v166, v167
	s_waitcnt lgkmcnt(1)
	v_pk_add_f32 v[168:169], v[76:77], v[168:169] op_sel:[0,1] op_sel_hi:[1,0]
	s_waitcnt lgkmcnt(0)
	v_pk_add_f32 v[170:171], v[78:79], v[170:171] op_sel:[0,1] op_sel_hi:[1,0]
	v_max3_f32 v0, v0, v168, v169
	v_max3_f32 v0, v0, v170, v171
	v_max3_f32 v0, v0, v88, v89
	v_max3_f32 v0, v0, v90, v91
	s_branch .LBB0_426

.LBB0_428:
	v_mul_f32_e32 v88, v80, v84
	v_mul_f32_e32 v89, v81, v84
	s_and_b64 vcc, exec, s[82:83]
	v_mul_f32_e32 v90, v82, v84
	v_mul_f32_e32 v91, v83, v84
	s_cbranch_vccnz .LBB0_430
	v_lshlrev_b32_e32 v80, 16, v130
	v_and_b32_e32 v81, 0xffff0000, v130
	v_fma_f32 v88, v86, v80, v88
	v_fma_f32 v89, v86, v81, v89
	v_lshlrev_b32_e32 v80, 16, v131
	v_and_b32_e32 v81, 0xffff0000, v131
	v_fma_f32 v90, v86, v80, v90
	v_fma_f32 v91, v86, v81, v91
.LBB0_430:
	s_ashr_i32 s34, s58, 11
	s_and_b32 s0, 0xffff, s0
	s_and_b32 s25, 0xffff, s47
	s_and_b32 s24, 0xffff, s24
	s_ashr_i32 s35, s34, 31
	v_lshl_add_u32 v80, s0, 7, v120
	s_lshr_b32 s48, s24, s25
	s_lshl_b64 s[24:25], s[34:35], 14
	v_ashrrev_i32_e32 v81, 31, v80
	v_lshlrev_b64 v[80:81], s57, v[80:81]
	s_or_b32 s24, s24, s48
	v_lshl_add_u64 v[80:81], s[24:25], 0, v[80:81]
	s_bfe_u32 s34, s58, 0x40007
	v_lshlrev_b64 v[82:83], 11, v[80:81]
	v_lshl_add_u64 v[82:83], s[96:97], 0, v[82:83]
	s_lshl_b32 s0, s34, 7
	v_mov_b32_e32 v85, v84
	v_lshl_add_u64 v[82:83], v[82:83], 0, s[0:1]
	v_lshlrev_b32_e32 v0, 1, v128
	v_lshl_add_u64 v[82:83], v[82:83], 0, v[0:1]
	v_cvt_pk_bf16_f32 v88, v88, v89
	v_cvt_pk_bf16_f32 v89, v90, v91
	v_mul_f32_e32 v72, v72, v84
	v_mul_f32_e32 v73, v73, v85
	s_and_b64 vcc, exec, s[82:83]
	v_mul_f32_e32 v74, v74, v84
	v_mul_f32_e32 v75, v75, v85
	global_store_dwordx2 v[82:83], v[88:89], off
	s_cbranch_vccnz .LBB0_432
	v_lshlrev_b32_e32 v88, 16, v118
	v_and_b32_e32 v89, 0xffff0000, v118
	v_fma_f32 v72, v86, v88, v72
	v_fma_f32 v73, v86, v89, v73
	v_lshlrev_b32_e32 v88, 16, v119
	v_and_b32_e32 v89, 0xffff0000, v119
	v_fma_f32 v74, v86, v88, v74
	v_fma_f32 v75, v86, v89, v75
.LBB0_432:
	v_cvt_pk_bf16_f32 v72, v72, v73
	v_cvt_pk_bf16_f32 v73, v74, v75
	v_mul_f32_e32 v68, v68, v84
	v_mul_f32_e32 v69, v69, v85
	s_and_b64 vcc, exec, s[82:83]
	v_mul_f32_e32 v70, v70, v84
	v_mul_f32_e32 v71, v71, v85
	global_store_dwordx2 v[82:83], v[72:73], off offset:32
	s_cbranch_vccnz .LBB0_434
	v_lshlrev_b32_e32 v72, 16, v116
	v_and_b32_e32 v73, 0xffff0000, v116
	v_fma_f32 v68, v86, v72, v68
	v_fma_f32 v69, v86, v73, v69
	v_lshlrev_b32_e32 v72, 16, v117
	v_and_b32_e32 v73, 0xffff0000, v117
	v_fma_f32 v70, v86, v72, v70
	v_fma_f32 v71, v86, v73, v71
.LBB0_434:
	v_cvt_pk_bf16_f32 v68, v68, v69
	v_cvt_pk_bf16_f32 v69, v70, v71
	global_store_dwordx2 v[82:83], v[68:69], off offset:64
	v_mul_f32_e32 v68, v76, v84
	v_mul_f32_e32 v69, v77, v85
	s_and_b64 vcc, exec, s[82:83]
	v_mul_f32_e32 v70, v78, v84
	v_mul_f32_e32 v71, v79, v85
	s_cbranch_vccnz .LBB0_436
	v_lshlrev_b32_e32 v72, 16, v114
	v_and_b32_e32 v73, 0xffff0000, v114
	v_fma_f32 v68, v86, v72, v68
	v_fma_f32 v69, v86, v73, v69
	v_lshlrev_b32_e32 v72, 16, v115
	v_and_b32_e32 v73, 0xffff0000, v115
	v_fma_f32 v70, v86, v72, v70
	v_fma_f32 v71, v86, v73, v71
